# scan S-update hand-scheduled: D/KD LDS reads issued 3 k-blocks ahead with counted lgkmcnt, ds_read_b64 from one base
# speedup vs baseline: 1.0094x; 1.0044x over previous
; #define LAS __attribute__((address_space(3)))
; __device__ __forceinline__ void hgrn_scan(const Params& p, LAS unsigned char* lds, int chain) {
;     ...
; #pragma unroll
;         for (int blk = 0; blk < 8; ++blk) {
;             const f32x4 d4 = *(const LAS f32x4*)(bb + SB_D + (16 * blk + 4 * g) * 4);
;             f32x4 s = S[blk] * d4;
; #pragma unroll
;             for (int sp = 0; sp < 2; ++sp) {
;                 const LAS unsigned char* kp = bb + SB_KD + (16 * blk + li) * HPK + (32 * sp + 4 * g) * 2;
;                 s = __builtin_amdgcn_mfma_f32_16x16x32_bf16(cat8u(*(const LAS u32x2*)kp, *(const LAS u32x2*)(kp + 32)), vf[sp], s, 0, 0, 0);
;             }
;             S[blk] = s;
;         }
.LBB0_412:
	v_add_u32_e32 v165, v140, v144
	v_add_u32_e32 v174, v140, v116
	ds_read_b128 v[180:183], v174 offset:50176
	ds_read_b64 v[184:185], v165 offset:20480
	ds_read_b64 v[186:187], v165 offset:20512
	ds_read_b64 v[188:189], v165 offset:20544
	ds_read_b64 v[190:191], v165 offset:20576
	ds_read_b128 v[192:195], v174 offset:50240
	ds_read_b64 v[196:197], v165 offset:22656
	ds_read_b64 v[198:199], v165 offset:22688
	ds_read_b64 v[200:201], v165 offset:22720
	ds_read_b64 v[202:203], v165 offset:22752
	s_waitcnt lgkmcnt(10)
	ds_read_b128 v[204:207], v174 offset:50304
	ds_read_b64 v[208:209], v165 offset:24832
	ds_read_b64 v[210:211], v165 offset:24864
	ds_read_b64 v[212:213], v165 offset:24896
	ds_read_b64 v[214:215], v165 offset:24928
	s_waitcnt lgkmcnt(5)
	v_pk_mul_f32 v[76:77], v[76:77], v[180:181]
	v_pk_mul_f32 v[78:79], v[78:79], v[182:183]
	v_pk_mul_f32 v[92:93], v[92:93], v[192:193]
	v_pk_mul_f32 v[94:95], v[94:95], v[194:195]
	v_mfma_f32_16x16x32_bf16 v[76:79], v[184:187], v[100:103], v[76:79]
	s_nop 0
	v_mfma_f32_16x16x32_bf16 v[92:95], v[196:199], v[100:103], v[92:95]
	v_mfma_f32_16x16x32_bf16 v[76:79], v[188:191], v[96:99], v[76:79]
	v_mfma_f32_16x16x32_bf16 v[92:95], v[200:203], v[96:99], v[92:95]
	ds_read_b128 v[180:183], v174 offset:50368
	ds_read_b64 v[184:185], v165 offset:27008
	ds_read_b64 v[186:187], v165 offset:27040
	ds_read_b64 v[188:189], v165 offset:27072
	ds_read_b64 v[190:191], v165 offset:27104
	ds_read_b128 v[192:195], v174 offset:50432
	ds_read_b64 v[196:197], v165 offset:29184
	ds_read_b64 v[198:199], v165 offset:29216
	ds_read_b64 v[200:201], v165 offset:29248
	ds_read_b64 v[202:203], v165 offset:29280
	s_waitcnt lgkmcnt(5)
	v_pk_mul_f32 v[80:81], v[80:81], v[204:205]
	v_pk_mul_f32 v[82:83], v[82:83], v[206:207]
	v_pk_mul_f32 v[88:89], v[88:89], v[180:181]
	v_pk_mul_f32 v[90:91], v[90:91], v[182:183]
	v_mfma_f32_16x16x32_bf16 v[80:83], v[208:211], v[100:103], v[80:83]
	s_nop 0
	v_mfma_f32_16x16x32_bf16 v[88:91], v[184:187], v[100:103], v[88:91]
	v_mfma_f32_16x16x32_bf16 v[80:83], v[212:215], v[96:99], v[80:83]
	v_mfma_f32_16x16x32_bf16 v[88:91], v[188:191], v[96:99], v[88:91]
	ds_read_b128 v[204:207], v174 offset:50496
	ds_read_b64 v[208:209], v165 offset:31360
	ds_read_b64 v[210:211], v165 offset:31392
	ds_read_b64 v[212:213], v165 offset:31424
	ds_read_b64 v[214:215], v165 offset:31456
	ds_read_b128 v[180:183], v174 offset:50560
	ds_read_b64 v[184:185], v165 offset:33536
	ds_read_b64 v[186:187], v165 offset:33568
	ds_read_b64 v[188:189], v165 offset:33600
	ds_read_b64 v[190:191], v165 offset:33632
	s_waitcnt lgkmcnt(5)
	v_pk_mul_f32 v[72:73], v[72:73], v[192:193]
	v_pk_mul_f32 v[74:75], v[74:75], v[194:195]
	v_pk_mul_f32 v[84:85], v[84:85], v[204:205]
	v_pk_mul_f32 v[86:87], v[86:87], v[206:207]
	v_mfma_f32_16x16x32_bf16 v[72:75], v[196:199], v[100:103], v[72:75]
	s_nop 0
	v_mfma_f32_16x16x32_bf16 v[84:87], v[208:211], v[100:103], v[84:87]
	v_mfma_f32_16x16x32_bf16 v[72:75], v[200:203], v[96:99], v[72:75]
	v_mfma_f32_16x16x32_bf16 v[84:87], v[212:215], v[96:99], v[84:87]
	ds_read_b128 v[192:195], v174 offset:50624
	ds_read_b64 v[196:197], v165 offset:35712
	ds_read_b64 v[198:199], v165 offset:35744
	ds_read_b64 v[200:201], v165 offset:35776
	ds_read_b64 v[202:203], v165 offset:35808
	s_waitcnt lgkmcnt(0)
	v_pk_mul_f32 v[64:65], v[64:65], v[180:181]
	v_pk_mul_f32 v[66:67], v[66:67], v[182:183]
	v_pk_mul_f32 v[68:69], v[68:69], v[192:193]
	v_pk_mul_f32 v[70:71], v[70:71], v[194:195]
	v_mfma_f32_16x16x32_bf16 v[64:67], v[184:187], v[100:103], v[64:67]
	s_nop 0
	v_mfma_f32_16x16x32_bf16 v[68:71], v[196:199], v[100:103], v[68:71]
	v_mfma_f32_16x16x32_bf16 v[64:67], v[188:191], v[96:99], v[64:67]
	v_mfma_f32_16x16x32_bf16 v[68:71], v[200:203], v[96:99], v[68:71]
	s_cmp_lt_u32 s23, 3
	s_cbranch_scc1 .LBB0_414
	s_waitcnt vmcnt(6)
	ds_write_b128 v158, v[40:43]
	s_waitcnt vmcnt(5)
	ds_write_b128 v158, v[44:47] offset:10240
	s_waitcnt vmcnt(4)
	ds_write_b128 v159, v[56:59]

; #define LAS __attribute__((address_space(3)))
; __device__ __forceinline__ void hgrn_scan(const Params& p, LAS unsigned char* lds, int chain) {
;     ...
; #pragma unroll
;         for (int blk = 0; blk < 8; ++blk) {
;             const f32x4 d4 = *(const LAS f32x4*)(bb + SB_D + (16 * blk + 4 * g) * 4);
;             f32x4 s = S[blk] * d4;
; #pragma unroll
;             for (int sp = 0; sp < 2; ++sp) {
;                 const LAS unsigned char* kp = bb + SB_KD + (16 * blk + li) * HPK + (32 * sp + 4 * g) * 2;
;                 s = __builtin_amdgcn_mfma_f32_16x16x32_bf16(cat8u(*(const LAS u32x2*)kp, *(const LAS u32x2*)(kp + 32)), vf[sp], s, 0, 0, 0);
;             }
;             S[blk] = s;
;         }
.LBB0_426:
	v_add_u32_e32 v165, v153, v144
	v_add_u32_e32 v174, 0x1d200, v143
	ds_read_b128 v[180:183], v174 offset:0
	ds_read_b64 v[184:185], v165 offset:0
	ds_read_b64 v[186:187], v165 offset:32
	ds_read_b64 v[188:189], v165 offset:64
	ds_read_b64 v[190:191], v165 offset:96
	ds_read_b128 v[192:195], v174 offset:64
	ds_read_b64 v[196:197], v165 offset:2176
	ds_read_b64 v[198:199], v165 offset:2208
	ds_read_b64 v[200:201], v165 offset:2240
	ds_read_b64 v[202:203], v165 offset:2272
	s_waitcnt lgkmcnt(10)
	ds_read_b128 v[204:207], v174 offset:128
	ds_read_b64 v[208:209], v165 offset:4352
	ds_read_b64 v[210:211], v165 offset:4384
	ds_read_b64 v[212:213], v165 offset:4416
	ds_read_b64 v[214:215], v165 offset:4448
	s_waitcnt lgkmcnt(5)
	v_pk_mul_f32 v[76:77], v[76:77], v[180:181]
	v_pk_mul_f32 v[78:79], v[78:79], v[182:183]
	v_pk_mul_f32 v[92:93], v[92:93], v[192:193]
	v_pk_mul_f32 v[94:95], v[94:95], v[194:195]
	v_mfma_f32_16x16x32_bf16 v[76:79], v[184:187], v[100:103], v[76:79]
	s_nop 0
	v_mfma_f32_16x16x32_bf16 v[92:95], v[196:199], v[100:103], v[92:95]
	v_mfma_f32_16x16x32_bf16 v[76:79], v[188:191], v[96:99], v[76:79]
	v_mfma_f32_16x16x32_bf16 v[92:95], v[200:203], v[96:99], v[92:95]
	ds_read_b128 v[180:183], v174 offset:192
	ds_read_b64 v[184:185], v165 offset:6528
	ds_read_b64 v[186:187], v165 offset:6560
	ds_read_b64 v[188:189], v165 offset:6592
	ds_read_b64 v[190:191], v165 offset:6624
	ds_read_b128 v[192:195], v174 offset:256
	ds_read_b64 v[196:197], v165 offset:8704
	ds_read_b64 v[198:199], v165 offset:8736
	ds_read_b64 v[200:201], v165 offset:8768
	ds_read_b64 v[202:203], v165 offset:8800
	s_waitcnt lgkmcnt(5)
	v_pk_mul_f32 v[80:81], v[80:81], v[204:205]
	v_pk_mul_f32 v[82:83], v[82:83], v[206:207]
	v_pk_mul_f32 v[88:89], v[88:89], v[180:181]
	v_pk_mul_f32 v[90:91], v[90:91], v[182:183]
	v_mfma_f32_16x16x32_bf16 v[80:83], v[208:211], v[100:103], v[80:83]
	s_nop 0
	v_mfma_f32_16x16x32_bf16 v[88:91], v[184:187], v[100:103], v[88:91]
	v_mfma_f32_16x16x32_bf16 v[80:83], v[212:215], v[96:99], v[80:83]
	v_mfma_f32_16x16x32_bf16 v[88:91], v[188:191], v[96:99], v[88:91]
	ds_read_b128 v[204:207], v174 offset:320
	ds_read_b64 v[208:209], v165 offset:10880
	ds_read_b64 v[210:211], v165 offset:10912
	ds_read_b64 v[212:213], v165 offset:10944
	ds_read_b64 v[214:215], v165 offset:10976
	ds_read_b128 v[180:183], v174 offset:384
	ds_read_b64 v[184:185], v165 offset:13056
	ds_read_b64 v[186:187], v165 offset:13088
	ds_read_b64 v[188:189], v165 offset:13120
	ds_read_b64 v[190:191], v165 offset:13152
	s_waitcnt lgkmcnt(5)
	v_pk_mul_f32 v[72:73], v[72:73], v[192:193]
	v_pk_mul_f32 v[74:75], v[74:75], v[194:195]
	v_pk_mul_f32 v[84:85], v[84:85], v[204:205]
	v_pk_mul_f32 v[86:87], v[86:87], v[206:207]
	v_mfma_f32_16x16x32_bf16 v[72:75], v[196:199], v[100:103], v[72:75]
	s_nop 0
	v_mfma_f32_16x16x32_bf16 v[84:87], v[208:211], v[100:103], v[84:87]
	v_mfma_f32_16x16x32_bf16 v[72:75], v[200:203], v[96:99], v[72:75]
	v_mfma_f32_16x16x32_bf16 v[84:87], v[212:215], v[96:99], v[84:87]
	ds_read_b128 v[192:195], v174 offset:448
	ds_read_b64 v[196:197], v165 offset:15232
	ds_read_b64 v[198:199], v165 offset:15264
	ds_read_b64 v[200:201], v165 offset:15296
	ds_read_b64 v[202:203], v165 offset:15328
	s_waitcnt lgkmcnt(0)
	v_pk_mul_f32 v[64:65], v[64:65], v[180:181]
	v_pk_mul_f32 v[66:67], v[66:67], v[182:183]
	v_pk_mul_f32 v[68:69], v[68:69], v[192:193]
	v_pk_mul_f32 v[70:71], v[70:71], v[194:195]
	v_mfma_f32_16x16x32_bf16 v[64:67], v[184:187], v[100:103], v[64:67]
	s_nop 0
	v_mfma_f32_16x16x32_bf16 v[68:71], v[196:199], v[100:103], v[68:71]
	v_mfma_f32_16x16x32_bf16 v[64:67], v[188:191], v[96:99], v[64:67]
	v_mfma_f32_16x16x32_bf16 v[68:71], v[200:203], v[96:99], v[68:71]
	s_add_i32 s12, s30, 3
	s_cmp_gt_u32 s12, 34
	s_cbranch_scc1 .LBB0_432
	s_cmp_eq_u32 s14, 0
	s_cbranch_scc1 .LBB0_429
	v_add_u32_e32 v96, v154, v113
	ds_write_b128 v96, v[48:51]
	ds_write_b128 v96, v[52:55] offset:10240
	ds_write_b128 v164, v[60:63] offset:40960
